# attention: branch-free per-quad selection of the stick-breaking carry (fma with per-lane 0/1 constants) on top of the packed adds / self-max removal / seam-0 change
# speedup vs baseline: 1.0046x; 1.0046x over previous
; #define LAS __attribute__((address_space(3)))
; __global__ void __launch_bounds__(512, 2) hybrid_fwd(Args a) {
;     extern __shared__ __attribute__((aligned(16))) unsigned char lds_raw[];
;     LAS unsigned char* lds = (LAS unsigned char*)lds_raw;
;     const int tid = threadIdx.x, lane = tid & 63, wid = __builtin_amdgcn_readfirstlane(tid >> 6);
;     const int lo = a.ph_lo, hi = a.ph_hi;
_Z10hybrid_fwd4Args:
	s_load_dwordx4 s[44:47], s[0:1], 0x90
	v_bfe_u32 v252, v0, 4, 1
	v_cvt_f32_u32_e32 v253, v252
	v_sub_f32_e32 v252, 1.0, v253
	v_bfe_u32 v254, v0, 5, 1
	v_cvt_f32_u32_e32 v255, v254
	v_sub_f32_e32 v254, 1.0, v255
	v_mov_b32_e32 v250, 1.0
	v_mov_b32_e32 v251, 1.0
	v_and_b32_e32 v202, 0x3ff, v0
	s_mov_b64 s[84:85], s[0:1]
	s_movk_i32 s0, 0x3ff
	v_readfirstlane_b32 s86, v202
	s_waitcnt lgkmcnt(0)
	s_getreg_b32 s98, hwreg(HW_REG_XCC_ID, 0, 4)
	v_cmp_eq_u32_e32 vcc, 0, v202
	s_and_saveexec_b64 s[4:5], vcc
	s_cbranch_execz .Lcensus_done
	s_add_u32 s6, s44, 0x1400
	s_addc_u32 s7, s45, 0
	s_lshl_b32 s3, s98, 2
	v_mov_b32_e32 v1, s3
	v_mov_b32_e32 v2, 1
	global_atomic_add v1, v1, v2, s[6:7] sc0
	s_waitcnt vmcnt(0)
	v_cmp_eq_u32_e32 vcc, 0, v1
	s_and_b64 exec, exec, vcc
	s_cbranch_execz .Lcensus_done
	v_mov_b32_e32 v1, 0
	global_atomic_add v1, v2, s[6:7] offset:64

; __device__ __forceinline__ void attn_unit(LAS unsigned char* lds, const bf16* P, bf16* Y, const float* gq, const float* gk, int b, int h, int qb, int tid, int wid, int lane, ...
;     ...
;                             const float x2 = r[3], x1 = x2 * r[2], x0 = x1 * r[1], T = x0 * r[0];
;                             const float A_ = __shfl_xor(T, 16), Bp = T * A_, Cc = __shfl_xor(Bp, 32);
;                             const float Xq = quad == 3 ? 1.0f : (quad == 2 ? A_ : (quad == 1 ? Cc : A_ * Cc));
;                             const float Yv = Xq * R;
;                             av[u][3] = be[3] * Yv; av[u][2] = be[2] * (x2 * Yv); av[u][1] = be[1] * (x1 * Yv); av[u][0] = be[0] * (x0 * Yv);
;                             R *= Bp * Cc;
.LBB0_335:
	v_mul_f32_e32 v47, v45, v44
	v_mul_f32_e32 v46, v49, v47
	v_mul_f32_e32 v44, v48, v46
	ds_bpermute_b32 v48, v99, v44
	s_waitcnt lgkmcnt(0)
	v_mul_f32_e32 v44, v44, v48
	ds_bpermute_b32 v50, v122, v44
	s_waitcnt lgkmcnt(0)
	v_fma_f32 v48, v48, v252, v253
	v_fma_f32 v49, v50, v254, v255
	v_mul_f32_e32 v49, v48, v49
	v_mul_f32_e32 v48, v45, v49
	v_pk_mul_f32 v[40:41], v[40:41], v[48:49]
	v_mov_b32_e32 v48, v49
	v_pk_mul_f32 v[46:47], v[46:47], v[48:49] op_sel_hi:[1,0]
	s_waitcnt lgkmcnt(0)
	v_mul_f32_e32 v69, v44, v50
	v_pk_mul_f32 v[42:43], v[42:43], v[46:47]
	s_branch .LBB0_344

; #define LAS __attribute__((address_space(3)))
; __device__ __forceinline__ unsigned pk2(float lo, float hi) { unsigned r; asm("v_cvt_pk_bf16_f32 %0, %1, %2" : "=v"(r) : "v"(lo), "v"(hi)); return r; }
; __device__ __forceinline__ f32x4 mfma16(bf16x8 a, bf16x8 b, f32x4 c) { return __builtin_amdgcn_mfma_f32_16x16x32_bf16(a, b, c, 0, 0, 0); }
; __device__ __forceinline__ void attn_unit(LAS unsigned char* lds, const bf16* P, bf16* Y, const float* gq, const float* gk, int b, int h, int qb, int tid, int wid, int lane, ...
;     ...
;                             const float x2 = r[3], x1 = x2 * r[2], x0 = x1 * r[1], T = x0 * r[0];
;                             const float A_ = __shfl_xor(T, 16), Bp = T * A_, Cc = __shfl_xor(Bp, 32);
;                             const float Xq = quad == 3 ? 1.0f : (quad == 2 ? A_ : (quad == 1 ? Cc : A_ * Cc));
;                             const float Yv = Xq * R;
;                             av[u][3] = be[3] * Yv; av[u][2] = be[2] * (x2 * Yv); av[u][1] = be[1] * (x1 * Yv); av[u][0] = be[0] * (x0 * Yv);
;                             R *= Bp * Cc;
;                         }
;                     }
;                     const bf16x8 Bf = mk8(pk2(av[0][0], av[0][1]), pk2(av[0][2], av[0][3]), pk2(av[1][0], av[1][1]), pk2(av[1][2], av[1][3]));
; #pragma unroll
;                     for (int dt = 0; dt < 4; ++dt) {
;                         const v2u lo = *(const LAS v2u*)(Vt + (16 * dt + tq) * 136 + 32 * p + 4 * quad), hi = *(const LAS v2u*)(Vt + (16 * dt + tq) * 136 + 32 * p + 16 + 4 * quad);
;                         O[dt] = mfma16(mk8(lo.x, lo.y, hi.x, hi.y), Bf, O[dt]);
;                     }
;                     if (__ballot(R >= 1e-20f) == 0ull) wdone = true;
.LBB0_346:
	v_mul_f32_e32 v44, v45, v44
	v_mul_f32_e32 v51, v51, v44
	v_mul_f32_e32 v50, v50, v51
	ds_bpermute_b32 v52, v99, v50
	s_waitcnt lgkmcnt(0)
	v_mul_f32_e32 v70, v50, v52
	ds_bpermute_b32 v71, v122, v70
	s_waitcnt lgkmcnt(0)
	v_fma_f32 v52, v52, v252, v253
	v_fma_f32 v50, v71, v254, v255
	v_mul_f32_e32 v50, v52, v50
	v_mul_f32_e32 v54, v69, v50
	v_mul_f32_e32 v50, v51, v54
	v_mul_f32_e32 v48, v48, v50
	v_add_u32_e32 v50, 0x4800, v131
	v_cvt_pk_bf16_f32 v75, v40, v41
	v_add_u32_e32 v40, 0x5800, v131
	ds_read2_b64 v[50:53], v50 offset0:24 offset1:28
	v_cvt_pk_bf16_f32 v74, v42, v43
	ds_read2_b64 v[40:43], v40 offset0:56 offset1:60
	v_mul_f32_e32 v44, v44, v54
	v_mul_f32_e32 v45, v45, v54
	v_mul_f32_e32 v44, v49, v44
	v_mul_f32_e32 v45, v46, v45
	v_mul_f32_e32 v46, v47, v54
	v_cvt_pk_bf16_f32 v72, v48, v44
	v_cvt_pk_bf16_f32 v73, v45, v46
	s_waitcnt lgkmcnt(2)
	v_mul_f32_e32 v70, v70, v71
	s_waitcnt lgkmcnt(1)
	v_mfma_f32_16x16x32_bf16 v[52:55], v[50:53], v[72:75], 0
	v_mul_f32_e32 v107, v69, v70
	v_cmp_le_f32_e32 vcc, s53, v107
	s_cmp_eq_u64 vcc, 0
	s_waitcnt lgkmcnt(0)
	v_mfma_f32_16x16x32_bf16 v[48:51], v[40:43], v[72:75], 0
	v_add_u32_e32 v40, 0x6800, v131
	ds_read2_b64 v[40:43], v40 offset0:88 offset1:92
	s_cselect_b64 s[12:13], -1, 0
	s_waitcnt lgkmcnt(0)
	v_mfma_f32_16x16x32_bf16 v[44:47], v[40:43], v[72:75], 0
	v_add_u32_e32 v40, 0x4800, v132
	ds_read2_b64 v[40:43], v40 offset0:24 offset1:28
	s_waitcnt lgkmcnt(0)
	v_mfma_f32_16x16x32_bf16 v[40:43], v[40:43], v[72:75], 0
	s_or_b64 s[10:11], s[22:23], s[12:13]
	s_and_b64 vcc, exec, s[10:11]
	s_cbranch_vccnz .LBB0_373

; __device__ __forceinline__ void attn_unit(LAS unsigned char* lds, const bf16* P, bf16* Y, const float* gq, const float* gk, int b, int h, int qb, int tid, int wid, int lane, ...
;     ...
;                             const float x2 = r[3], x1 = x2 * r[2], x0 = x1 * r[1], T = x0 * r[0];
;                             const float A_ = __shfl_xor(T, 16), Bp = T * A_, Cc = __shfl_xor(Bp, 32);
;                             const float Xq = quad == 3 ? 1.0f : (quad == 2 ? A_ : (quad == 1 ? Cc : A_ * Cc));
;                             const float Yv = Xq * R;
;                             av[u][3] = be[3] * Yv; av[u][2] = be[2] * (x2 * Yv); av[u][1] = be[1] * (x1 * Yv); av[u][0] = be[0] * (x0 * Yv);
;                             R *= Bp * Cc;
.LBB0_356:
	v_mul_f32_e32 v77, v75, v74
	v_mul_f32_e32 v76, v79, v77
	v_mul_f32_e32 v69, v78, v76
	ds_bpermute_b32 v79, v99, v69
	s_waitcnt lgkmcnt(0)
	v_mul_f32_e32 v69, v69, v79
	ds_bpermute_b32 v74, v122, v69
	s_waitcnt lgkmcnt(0)
	v_fma_f32 v79, v79, v252, v253
	v_fma_f32 v78, v74, v254, v255
	v_mul_f32_e32 v78, v79, v78
	v_mul_f32_e32 v79, v107, v78
	v_mul_f32_e32 v78, v75, v79
	v_pk_mul_f32 v[70:71], v[70:71], v[78:79]
	v_mov_b32_e32 v78, v79
	v_pk_mul_f32 v[76:77], v[76:77], v[78:79] op_sel_hi:[1,0]
	s_waitcnt lgkmcnt(0)
	v_mul_f32_e32 v69, v69, v74
	v_pk_mul_f32 v[72:73], v[72:73], v[76:77]
	v_mul_f32_e32 v107, v107, v69
	s_branch .LBB0_364

; #define LAS __attribute__((address_space(3)))
; __device__ __forceinline__ unsigned pk2(float lo, float hi) { unsigned r; asm("v_cvt_pk_bf16_f32 %0, %1, %2" : "=v"(r) : "v"(lo), "v"(hi)); return r; }
; __device__ __forceinline__ f32x4 mfma16(bf16x8 a, bf16x8 b, f32x4 c) { return __builtin_amdgcn_mfma_f32_16x16x32_bf16(a, b, c, 0, 0, 0); }
; __device__ __forceinline__ void attn_unit(LAS unsigned char* lds, const bf16* P, bf16* Y, const float* gq, const float* gk, int b, int h, int qb, int tid, int wid, int lane, ...
;     ...
;                             const float x2 = r[3], x1 = x2 * r[2], x0 = x1 * r[1], T = x0 * r[0];
;                             const float A_ = __shfl_xor(T, 16), Bp = T * A_, Cc = __shfl_xor(Bp, 32);
;                             const float Xq = quad == 3 ? 1.0f : (quad == 2 ? A_ : (quad == 1 ? Cc : A_ * Cc));
;                             const float Yv = Xq * R;
;                             av[u][3] = be[3] * Yv; av[u][2] = be[2] * (x2 * Yv); av[u][1] = be[1] * (x1 * Yv); av[u][0] = be[0] * (x0 * Yv);
;                             R *= Bp * Cc;
;                         }
;                     }
;                     const bf16x8 Bf = mk8(pk2(av[0][0], av[0][1]), pk2(av[0][2], av[0][3]), pk2(av[1][0], av[1][1]), pk2(av[1][2], av[1][3]));
; #pragma unroll
;                     for (int dt = 0; dt < 4; ++dt) {
;                         const v2u lo = *(const LAS v2u*)(Vt + (16 * dt + tq) * 136 + 32 * p + 4 * quad), hi = *(const LAS v2u*)(Vt + (16 * dt + tq) * 136 + 32 * p + 16 + 4 * quad);
;                         O[dt] = mfma16(mk8(lo.x, lo.y, hi.x, hi.y), Bf, O[dt]);
;                     }
;                     if (__ballot(R >= 1e-20f) == 0ull) wdone = true;
.LBB0_366:
	v_mul_f32_e32 v82, v75, v74
	v_mul_f32_e32 v81, v81, v82
	v_mul_f32_e32 v69, v80, v81
	ds_bpermute_b32 v83, v99, v69
	s_waitcnt lgkmcnt(0)
	v_mul_f32_e32 v69, v69, v83
	ds_bpermute_b32 v74, v122, v69
	s_waitcnt lgkmcnt(0)
	v_fma_f32 v83, v83, v252, v253
	v_fma_f32 v80, v74, v254, v255
	v_mul_f32_e32 v80, v83, v80
	v_mul_f32_e32 v105, v107, v80
	v_mul_f32_e32 v143, v82, v105
	v_mul_f32_e32 v80, v81, v105
	v_mul_f32_e32 v79, v79, v143
	v_mul_f32_e32 v75, v75, v105
	v_mul_f32_e32 v78, v78, v80
	v_mul_f32_e32 v75, v76, v75
	v_cvt_pk_bf16_f32 v76, v78, v79
	v_cvt_pk_bf16_f32 v79, v70, v71
	v_add_u32_e32 v70, 0x5800, v131
	v_cvt_pk_bf16_f32 v78, v72, v73
	ds_read2_b64 v[70:73], v70 offset0:48 offset1:52
	v_mul_f32_e32 v77, v77, v105
	v_cvt_pk_bf16_f32 v77, v75, v77
	v_add_u32_e32 v80, 0x4800, v131
	ds_read2_b64 v[80:83], v80 offset0:16 offset1:20
	s_waitcnt lgkmcnt(1)
	v_mfma_f32_16x16x32_bf16 v[48:51], v[70:73], v[76:79], v[48:51]
	v_add_u32_e32 v70, 0x6800, v131
	ds_read2_b64 v[70:73], v70 offset0:80 offset1:84
	v_mul_f32_e32 v69, v69, v74
	s_waitcnt lgkmcnt(0)
	v_mfma_f32_16x16x32_bf16 v[44:47], v[70:73], v[76:79], v[44:47]
	v_add_u32_e32 v70, 0x4800, v132
	ds_read2_b64 v[70:73], v70 offset0:16 offset1:20
	v_mul_f32_e32 v107, v107, v69
	v_mfma_f32_16x16x32_bf16 v[52:55], v[80:83], v[76:79], v[52:55]
	v_cmp_le_f32_e32 vcc, s53, v107
	s_cmp_eq_u64 vcc, 0
	s_cselect_b64 s[12:13], -1, 0
	s_waitcnt lgkmcnt(0)
	v_mfma_f32_16x16x32_bf16 v[40:43], v[70:73], v[76:79], v[40:43]

; __device__ __forceinline__ void attn_unit(LAS unsigned char* lds, const bf16* P, bf16* Y, const float* gq, const float* gk, int b, int h, int qb, int tid, int wid, int lane, ...
;     ...
;                             const float x2 = r[3], x1 = x2 * r[2], x0 = x1 * r[1], T = x0 * r[0];
;                             const float A_ = __shfl_xor(T, 16), Bp = T * A_, Cc = __shfl_xor(Bp, 32);
;                             const float Xq = quad == 3 ? 1.0f : (quad == 2 ? A_ : (quad == 1 ? Cc : A_ * Cc));
;                             const float Yv = Xq * R;
;                             av[u][3] = be[3] * Yv; av[u][2] = be[2] * (x2 * Yv); av[u][1] = be[1] * (x1 * Yv); av[u][0] = be[0] * (x0 * Yv);
;                             R *= Bp * Cc;
.LBB0_390:
	v_mul_f32_e32 v65, v57, v56
	v_mul_f32_e32 v64, v63, v65
	v_mul_f32_e32 v56, v62, v64
	ds_bpermute_b32 v66, v99, v56
	s_waitcnt lgkmcnt(0)
	v_mul_f32_e32 v62, v56, v66
	ds_bpermute_b32 v63, v122, v62
	s_waitcnt lgkmcnt(0)
	v_fma_f32 v66, v66, v252, v253
	v_fma_f32 v56, v63, v254, v255
	v_mul_f32_e32 v56, v66, v56
	v_mul_f32_e32 v67, v107, v56
	v_mul_f32_e32 v66, v57, v67
	v_pk_mul_f32 v[56:57], v[60:61], v[66:67]
	v_mov_b32_e32 v60, v67
	v_pk_mul_f32 v[60:61], v[64:65], v[60:61] op_sel_hi:[1,0]
	s_nop 0
	v_pk_mul_f32 v[58:59], v[58:59], v[60:61]
	s_waitcnt lgkmcnt(0)
	v_mul_f32_e32 v60, v62, v63
	v_mul_f32_e32 v107, v107, v60
	s_branch .LBB0_398

; #define LAS __attribute__((address_space(3)))
; __device__ __forceinline__ unsigned pk2(float lo, float hi) { unsigned r; asm("v_cvt_pk_bf16_f32 %0, %1, %2" : "=v"(r) : "v"(lo), "v"(hi)); return r; }
; __device__ __forceinline__ f32x4 mfma16(bf16x8 a, bf16x8 b, f32x4 c) { return __builtin_amdgcn_mfma_f32_16x16x32_bf16(a, b, c, 0, 0, 0); }
; __device__ __forceinline__ void attn_unit(LAS unsigned char* lds, const bf16* P, bf16* Y, const float* gq, const float* gk, int b, int h, int qb, int tid, int wid, int lane, ...
;     ...
;                             const float x2 = r[3], x1 = x2 * r[2], x0 = x1 * r[1], T = x0 * r[0];
;                             const float A_ = __shfl_xor(T, 16), Bp = T * A_, Cc = __shfl_xor(Bp, 32);
;                             const float Xq = quad == 3 ? 1.0f : (quad == 2 ? A_ : (quad == 1 ? Cc : A_ * Cc));
;                             const float Yv = Xq * R;
;                             av[u][3] = be[3] * Yv; av[u][2] = be[2] * (x2 * Yv); av[u][1] = be[1] * (x1 * Yv); av[u][0] = be[0] * (x0 * Yv);
;                             R *= Bp * Cc;
;                         }
;                     }
;                     const bf16x8 Bf = mk8(pk2(av[0][0], av[0][1]), pk2(av[0][2], av[0][3]), pk2(av[1][0], av[1][1]), pk2(av[1][2], av[1][3]));
; #pragma unroll
;                     for (int dt = 0; dt < 4; ++dt) {
;                         const v2u lo = *(const LAS v2u*)(Vt + (16 * dt + tq) * 136 + 32 * p + 4 * quad), hi = *(const LAS v2u*)(Vt + (16 * dt + tq) * 136 + 32 * p + 16 + 4 * quad);
;                         O[dt] = mfma16(mk8(lo.x, lo.y, hi.x, hi.y), Bf, O[dt]);
;                     }
;                     if (__ballot(R >= 1e-20f) == 0ull) wdone = true;
.LBB0_400:
	v_mul_f32_e32 v60, v61, v60
	v_mul_f32_e32 v67, v67, v60
	v_mul_f32_e32 v66, v66, v67
	ds_bpermute_b32 v86, v99, v66
	s_waitcnt lgkmcnt(0)
	v_mul_f32_e32 v84, v66, v86
	ds_bpermute_b32 v85, v122, v84
	s_waitcnt lgkmcnt(0)
	v_fma_f32 v86, v86, v252, v253
	v_fma_f32 v66, v85, v254, v255
	v_mul_f32_e32 v66, v86, v66
	v_mul_f32_e32 v66, v107, v66
	v_mul_f32_e32 v61, v61, v66
	v_mul_f32_e32 v61, v62, v61
	v_mul_f32_e32 v62, v63, v66
	v_cvt_pk_bf16_f32 v63, v56, v57
	v_add_u32_e32 v56, 0x4800, v131
	v_cvt_pk_bf16_f32 v61, v61, v62
	v_cvt_pk_bf16_f32 v62, v58, v59
	ds_read2_b64 v[56:59], v56 offset0:24 offset1:28
	v_mul_f32_e32 v60, v60, v66
	v_mul_f32_e32 v67, v67, v66
	v_mul_f32_e32 v60, v65, v60
	v_mul_f32_e32 v64, v64, v67
	v_cvt_pk_bf16_f32 v60, v64, v60
	s_waitcnt lgkmcnt(1)
	v_mul_f32_e32 v84, v84, v85
	s_waitcnt lgkmcnt(0)
	v_mfma_f32_16x16x32_bf16 v[52:55], v[56:59], v[60:63], v[52:55]
	v_add_u32_e32 v56, 0x5800, v131
	ds_read2_b64 v[56:59], v56 offset0:56 offset1:60
	v_mul_f32_e32 v84, v107, v84
	v_cmp_le_f32_e32 vcc, s53, v84
	s_waitcnt lgkmcnt(0)
	v_mfma_f32_16x16x32_bf16 v[48:51], v[56:59], v[60:63], v[48:51]
	v_add_u32_e32 v56, 0x6800, v131
	ds_read2_b64 v[56:59], v56 offset0:88 offset1:92
	s_cmp_eq_u64 vcc, 0
	s_waitcnt lgkmcnt(0)
	v_mfma_f32_16x16x32_bf16 v[44:47], v[56:59], v[60:63], v[44:47]
	v_add_u32_e32 v56, 0x4800, v132
	ds_read2_b64 v[56:59], v56 offset0:24 offset1:28
	s_cselect_b64 s[10:11], -1, 0
	s_waitcnt lgkmcnt(0)
	v_mfma_f32_16x16x32_bf16 v[40:43], v[56:59], v[60:63], v[40:43]
	v_mov_b32_e32 v107, v84

; #define LAS __attribute__((address_space(3)))
; __device__ __forceinline__ unsigned pk2(float lo, float hi) { unsigned r; asm("v_cvt_pk_bf16_f32 %0, %1, %2" : "=v"(r) : "v"(lo), "v"(hi)); return r; }
; __device__ __forceinline__ f32x4 mfma16(bf16x8 a, bf16x8 b, f32x4 c) { return __builtin_amdgcn_mfma_f32_16x16x32_bf16(a, b, c, 0, 0, 0); }
; __device__ __forceinline__ void attn_unit(LAS unsigned char* lds, const bf16* P, bf16* Y, const float* gq, const float* gk, int b, int h, int qb, int tid, int wid, int lane, ...
;     ...
;                             const float x2 = r[3], x1 = x2 * r[2], x0 = x1 * r[1], T = x0 * r[0];
;                             const float A_ = __shfl_xor(T, 16), Bp = T * A_, Cc = __shfl_xor(Bp, 32);
;                             const float Xq = quad == 3 ? 1.0f : (quad == 2 ? A_ : (quad == 1 ? Cc : A_ * Cc));
;                             const float Yv = Xq * R;
;                             av[u][3] = be[3] * Yv; av[u][2] = be[2] * (x2 * Yv); av[u][1] = be[1] * (x1 * Yv); av[u][0] = be[0] * (x0 * Yv);
;                             R *= Bp * Cc;
;                         }
;                     }
;                     const bf16x8 Bf = mk8(pk2(av[0][0], av[0][1]), pk2(av[0][2], av[0][3]), pk2(av[1][0], av[1][1]), pk2(av[1][2], av[1][3]));
; #pragma unroll
;                     for (int dt = 0; dt < 4; ++dt) {
;                         const v2u lo = *(const LAS v2u*)(Vt + (16 * dt + tq) * 136 + 32 * p + 4 * quad), hi = *(const LAS v2u*)(Vt + (16 * dt + tq) * 136 + 32 * p + 16 + 4 * quad);
;                         O[dt] = mfma16(mk8(lo.x, lo.y, hi.x, hi.y), Bf, O[dt]);
;                     }
;                     if (__ballot(R >= 1e-20f) == 0ull) wdone = true;
.LBB0_421:
	v_mul_f32_e32 v60, v61, v60
	v_mul_f32_e32 v67, v67, v60
	v_mul_f32_e32 v66, v66, v67
	ds_bpermute_b32 v86, v99, v66
	s_waitcnt lgkmcnt(0)
	v_mul_f32_e32 v84, v66, v86
	ds_bpermute_b32 v85, v122, v84
	s_waitcnt lgkmcnt(0)
	v_fma_f32 v86, v86, v252, v253
	v_fma_f32 v66, v85, v254, v255
	v_mul_f32_e32 v66, v86, v66
	v_mul_f32_e32 v66, v107, v66
	v_mul_f32_e32 v61, v61, v66
	v_mul_f32_e32 v61, v62, v61
	v_mul_f32_e32 v62, v63, v66
	v_cvt_pk_bf16_f32 v63, v56, v57
	v_add_u32_e32 v56, 0x4800, v131
	v_cvt_pk_bf16_f32 v61, v61, v62
	v_cvt_pk_bf16_f32 v62, v58, v59
	ds_read2_b64 v[56:59], v56 offset0:16 offset1:20
	v_mul_f32_e32 v60, v60, v66
	v_mul_f32_e32 v67, v67, v66
	v_mul_f32_e32 v60, v65, v60
	v_mul_f32_e32 v64, v64, v67
	v_cvt_pk_bf16_f32 v60, v64, v60
	s_waitcnt lgkmcnt(1)
	v_mul_f32_e32 v84, v84, v85
	s_waitcnt lgkmcnt(0)
	v_mfma_f32_16x16x32_bf16 v[52:55], v[56:59], v[60:63], v[52:55]
	v_add_u32_e32 v56, 0x5800, v131
	ds_read2_b64 v[56:59], v56 offset0:48 offset1:52
	v_mul_f32_e32 v84, v107, v84
	v_cmp_le_f32_e32 vcc, s53, v84
	s_waitcnt lgkmcnt(0)
	v_mfma_f32_16x16x32_bf16 v[48:51], v[56:59], v[60:63], v[48:51]
	v_add_u32_e32 v56, 0x6800, v131
	ds_read2_b64 v[56:59], v56 offset0:80 offset1:84
	s_cmp_eq_u64 vcc, 0
	s_waitcnt lgkmcnt(0)
	v_mfma_f32_16x16x32_bf16 v[44:47], v[56:59], v[60:63], v[44:47]
	v_add_u32_e32 v56, 0x4800, v132
	ds_read2_b64 v[56:59], v56 offset0:16 offset1:20
	s_cselect_b64 s[10:11], -1, 0
	s_waitcnt lgkmcnt(0)
	v_mfma_f32_16x16x32_bf16 v[40:43], v[56:59], v[60:63], v[40:43]
	v_mov_b32_e32 v107, v84

; #define LAS __attribute__((address_space(3)))
; __device__ __forceinline__ unsigned pk2(float lo, float hi) { unsigned r; asm("v_cvt_pk_bf16_f32 %0, %1, %2" : "=v"(r) : "v"(lo), "v"(hi)); return r; }
; __device__ __forceinline__ f32x4 mfma16(bf16x8 a, bf16x8 b, f32x4 c) { return __builtin_amdgcn_mfma_f32_16x16x32_bf16(a, b, c, 0, 0, 0); }
; __device__ __forceinline__ void attn_unit(LAS unsigned char* lds, const bf16* P, bf16* Y, const float* gq, const float* gk, int b, int h, int qb, int tid, int wid, int lane, ...
;     ...
;                             const float x2 = r[3], x1 = x2 * r[2], x0 = x1 * r[1], T = x0 * r[0];
;                             const float A_ = __shfl_xor(T, 16), Bp = T * A_, Cc = __shfl_xor(Bp, 32);
;                             const float Xq = quad == 3 ? 1.0f : (quad == 2 ? A_ : (quad == 1 ? Cc : A_ * Cc));
;                             const float Yv = Xq * R;
;                             av[u][3] = be[3] * Yv; av[u][2] = be[2] * (x2 * Yv); av[u][1] = be[1] * (x1 * Yv); av[u][0] = be[0] * (x0 * Yv);
;                             R *= Bp * Cc;
;                         }
;                     }
;                     const bf16x8 Bf = mk8(pk2(av[0][0], av[0][1]), pk2(av[0][2], av[0][3]), pk2(av[1][0], av[1][1]), pk2(av[1][2], av[1][3]));
; #pragma unroll
;                     for (int dt = 0; dt < 4; ++dt) {
;                         const v2u lo = *(const LAS v2u*)(Vt + (16 * dt + tq) * 136 + 32 * p + 4 * quad), hi = *(const LAS v2u*)(Vt + (16 * dt + tq) * 136 + 32 * p + 16 + 4 * quad);
;                         O[dt] = mfma16(mk8(lo.x, lo.y, hi.x, hi.y), Bf, O[dt]);
;                     }
;                     if (__ballot(R >= 1e-20f) == 0ull) wdone = true;
.LBB0_442:
	v_mul_f32_e32 v60, v61, v60
	v_mul_f32_e32 v67, v67, v60
	v_mul_f32_e32 v66, v66, v67
	ds_bpermute_b32 v86, v99, v66
	s_waitcnt lgkmcnt(0)
	v_mul_f32_e32 v84, v66, v86
	ds_bpermute_b32 v85, v122, v84
	s_waitcnt lgkmcnt(0)
	v_fma_f32 v86, v86, v252, v253
	v_fma_f32 v66, v85, v254, v255
	v_mul_f32_e32 v66, v86, v66
	v_mul_f32_e32 v66, v107, v66
	v_mul_f32_e32 v61, v61, v66
	v_mul_f32_e32 v61, v62, v61
	v_mul_f32_e32 v62, v63, v66
	v_cvt_pk_bf16_f32 v63, v56, v57
	v_add_u32_e32 v56, 0x4800, v131
	v_cvt_pk_bf16_f32 v61, v61, v62
	v_cvt_pk_bf16_f32 v62, v58, v59
	ds_read2_b64 v[56:59], v56 offset0:8 offset1:12
	v_mul_f32_e32 v60, v60, v66
	v_mul_f32_e32 v67, v67, v66
	v_mul_f32_e32 v60, v65, v60
	v_mul_f32_e32 v64, v64, v67
	v_cvt_pk_bf16_f32 v60, v64, v60
	s_waitcnt lgkmcnt(1)
	v_mul_f32_e32 v84, v84, v85
	s_waitcnt lgkmcnt(0)
	v_mfma_f32_16x16x32_bf16 v[52:55], v[56:59], v[60:63], v[52:55]
	v_add_u32_e32 v56, 0x5800, v131
	ds_read2_b64 v[56:59], v56 offset0:40 offset1:44
	v_mul_f32_e32 v84, v107, v84
	v_cmp_le_f32_e32 vcc, s53, v84
	s_waitcnt lgkmcnt(0)
	v_mfma_f32_16x16x32_bf16 v[48:51], v[56:59], v[60:63], v[48:51]
	v_add_u32_e32 v56, 0x4800, v133
	ds_read2_b64 v[56:59], v56 offset0:8 offset1:12
	s_cmp_eq_u64 vcc, 0
	s_waitcnt lgkmcnt(0)
	v_mfma_f32_16x16x32_bf16 v[44:47], v[56:59], v[60:63], v[44:47]
	v_add_u32_e32 v56, 0x4800, v132
	ds_read2_b64 v[56:59], v56 offset0:8 offset1:12
	s_cselect_b64 s[10:11], -1, 0
	s_waitcnt lgkmcnt(0)
	v_mfma_f32_16x16x32_bf16 v[40:43], v[56:59], v[60:63], v[40:43]
	v_mov_b32_e32 v107, v84

; #define LAS __attribute__((address_space(3)))
; __device__ __forceinline__ unsigned pk2(float lo, float hi) { unsigned r; asm("v_cvt_pk_bf16_f32 %0, %1, %2" : "=v"(r) : "v"(lo), "v"(hi)); return r; }
; __device__ __forceinline__ f32x4 mfma16(bf16x8 a, bf16x8 b, f32x4 c) { return __builtin_amdgcn_mfma_f32_16x16x32_bf16(a, b, c, 0, 0, 0); }
; __device__ __forceinline__ void attn_unit(LAS unsigned char* lds, const bf16* P, bf16* Y, const float* gq, const float* gk, int b, int h, int qb, int tid, int wid, int lane, ...
;     ...
;                             const float x2 = r[3], x1 = x2 * r[2], x0 = x1 * r[1], T = x0 * r[0];
;                             const float A_ = __shfl_xor(T, 16), Bp = T * A_, Cc = __shfl_xor(Bp, 32);
;                             const float Xq = quad == 3 ? 1.0f : (quad == 2 ? A_ : (quad == 1 ? Cc : A_ * Cc));
;                             const float Yv = Xq * R;
;                             av[u][3] = be[3] * Yv; av[u][2] = be[2] * (x2 * Yv); av[u][1] = be[1] * (x1 * Yv); av[u][0] = be[0] * (x0 * Yv);
;                             R *= Bp * Cc;
;                         }
;                     }
;                     const bf16x8 Bf = mk8(pk2(av[0][0], av[0][1]), pk2(av[0][2], av[0][3]), pk2(av[1][0], av[1][1]), pk2(av[1][2], av[1][3]));
; #pragma unroll
;                     for (int dt = 0; dt < 4; ++dt) {
;                         const v2u lo = *(const LAS v2u*)(Vt + (16 * dt + tq) * 136 + 32 * p + 4 * quad), hi = *(const LAS v2u*)(Vt + (16 * dt + tq) * 136 + 32 * p + 16 + 4 * quad);
;                         O[dt] = mfma16(mk8(lo.x, lo.y, hi.x, hi.y), Bf, O[dt]);
;                     }
;                     if (__ballot(R >= 1e-20f) == 0ull) wdone = true;
.LBB0_463:
	v_mul_f32_e32 v84, v61, v60
	v_mul_f32_e32 v67, v67, v84
	v_mul_f32_e32 v60, v66, v67
	ds_bpermute_b32 v86, v99, v60
	s_waitcnt lgkmcnt(0)
	v_mul_f32_e32 v60, v60, v86
	ds_bpermute_b32 v66, v122, v60
	s_waitcnt lgkmcnt(0)
	v_fma_f32 v86, v86, v252, v253
	v_fma_f32 v85, v66, v254, v255
	v_mul_f32_e32 v85, v86, v85
	v_mul_f32_e32 v105, v107, v85
	v_mul_f32_e32 v67, v67, v105
	v_mul_f32_e32 v64, v64, v67
	v_mul_f32_e32 v67, v84, v105
	v_mul_f32_e32 v65, v65, v67
	v_mul_f32_e32 v61, v61, v105
	v_mul_f32_e32 v61, v62, v61
	v_cvt_pk_bf16_f32 v62, v64, v65
	v_cvt_pk_bf16_f32 v65, v56, v57
	v_add_u32_e32 v56, 0x5800, v131
	v_cvt_pk_bf16_f32 v64, v58, v59
	ds_read2_b64 v[56:59], v56 offset0:32 offset1:36
	v_mul_f32_e32 v63, v63, v105
	v_cvt_pk_bf16_f32 v63, v61, v63
	v_add_u32_e32 v84, 0x4800, v131
	ds_read2_b64 v[84:87], v84 offset1:4
	s_waitcnt lgkmcnt(1)
	v_mfma_f32_16x16x32_bf16 v[48:51], v[56:59], v[62:65], v[48:51]
	v_add_u32_e32 v56, 0x6800, v131
	ds_read2_b64 v[56:59], v56 offset0:64 offset1:68
	v_mul_f32_e32 v60, v60, v66
	s_waitcnt lgkmcnt(0)
	v_mfma_f32_16x16x32_bf16 v[44:47], v[56:59], v[62:65], v[44:47]
	v_add_u32_e32 v56, 0x4800, v132
	ds_read2_b64 v[56:59], v56 offset1:4
	v_mul_f32_e32 v107, v107, v60
	v_mfma_f32_16x16x32_bf16 v[52:55], v[84:87], v[62:65], v[52:55]
	v_cmp_le_f32_e32 vcc, s53, v107
	s_cmp_eq_u64 vcc, 0
	s_cselect_b64 s[10:11], -1, 0
	s_waitcnt lgkmcnt(0)
	v_mfma_f32_16x16x32_bf16 v[40:43], v[56:59], v[62:65], v[40:43]

; #define LAS __attribute__((address_space(3)))
; __device__ __forceinline__ unsigned pk2(float lo, float hi) { unsigned r; asm("v_cvt_pk_bf16_f32 %0, %1, %2" : "=v"(r) : "v"(lo), "v"(hi)); return r; }
; __device__ __forceinline__ f32x4 mfma16(bf16x8 a, bf16x8 b, f32x4 c) { return __builtin_amdgcn_mfma_f32_16x16x32_bf16(a, b, c, 0, 0, 0); }
; __device__ __forceinline__ void attn_unit(LAS unsigned char* lds, const bf16* P, bf16* Y, const float* gq, const float* gk, int b, int h, int qb, int tid, int wid, int lane, ...
;     ...
;                             const float x2 = r[3], x1 = x2 * r[2], x0 = x1 * r[1], T = x0 * r[0];
;                             const float A_ = __shfl_xor(T, 16), Bp = T * A_, Cc = __shfl_xor(Bp, 32);
;                             const float Xq = quad == 3 ? 1.0f : (quad == 2 ? A_ : (quad == 1 ? Cc : A_ * Cc));
;                             const float Yv = Xq * R;
;                             av[u][3] = be[3] * Yv; av[u][2] = be[2] * (x2 * Yv); av[u][1] = be[1] * (x1 * Yv); av[u][0] = be[0] * (x0 * Yv);
;                             R *= Bp * Cc;
;                         }
;                     }
;                     const bf16x8 Bf = mk8(pk2(av[0][0], av[0][1]), pk2(av[0][2], av[0][3]), pk2(av[1][0], av[1][1]), pk2(av[1][2], av[1][3]));
; #pragma unroll
;                     for (int dt = 0; dt < 4; ++dt) {
;                         const v2u lo = *(const LAS v2u*)(Vt + (16 * dt + tq) * 136 + 32 * p + 4 * quad), hi = *(const LAS v2u*)(Vt + (16 * dt + tq) * 136 + 32 * p + 16 + 4 * quad);
;                         O[dt] = mfma16(mk8(lo.x, lo.y, hi.x, hi.y), Bf, O[dt]);
;                     }
;                     if (__ballot(R >= 1e-20f) == 0ull) wdone = true;
.LBB0_498:
	v_mul_f32_e32 v82, v75, v74
	v_mul_f32_e32 v81, v81, v82
	v_mul_f32_e32 v69, v80, v81
	ds_bpermute_b32 v83, v99, v69
	s_waitcnt lgkmcnt(0)
	v_mul_f32_e32 v69, v69, v83
	ds_bpermute_b32 v74, v122, v69
	s_waitcnt lgkmcnt(0)
	v_fma_f32 v83, v83, v252, v253
	v_fma_f32 v80, v74, v254, v255
	v_mul_f32_e32 v80, v83, v80
	v_mul_f32_e32 v105, v107, v80
	v_mul_f32_e32 v143, v82, v105
	v_mul_f32_e32 v80, v81, v105
	v_mul_f32_e32 v79, v79, v143
	v_mul_f32_e32 v75, v75, v105
	v_mul_f32_e32 v78, v78, v80
	v_mul_f32_e32 v75, v76, v75
	v_cvt_pk_bf16_f32 v76, v78, v79
	v_cvt_pk_bf16_f32 v79, v70, v71
	v_add_u32_e32 v70, 0x5800, v131
	v_cvt_pk_bf16_f32 v78, v72, v73
	ds_read2_b64 v[70:73], v70 offset0:40 offset1:44
	v_mul_f32_e32 v77, v77, v105
	v_cvt_pk_bf16_f32 v77, v75, v77
	v_add_u32_e32 v80, 0x4800, v131
	ds_read2_b64 v[80:83], v80 offset0:8 offset1:12
	s_waitcnt lgkmcnt(1)
	v_mfma_f32_16x16x32_bf16 v[48:51], v[70:73], v[76:79], v[48:51]
	v_add_u32_e32 v70, 0x4800, v133
	ds_read2_b64 v[70:73], v70 offset0:8 offset1:12
	v_mul_f32_e32 v69, v69, v74
	s_waitcnt lgkmcnt(0)
	v_mfma_f32_16x16x32_bf16 v[44:47], v[70:73], v[76:79], v[44:47]
	v_add_u32_e32 v70, 0x4800, v132
	ds_read2_b64 v[70:73], v70 offset0:8 offset1:12
	v_mul_f32_e32 v107, v107, v69
	v_mfma_f32_16x16x32_bf16 v[52:55], v[80:83], v[76:79], v[52:55]
	v_cmp_le_f32_e32 vcc, s53, v107
	s_cmp_eq_u64 vcc, 0
	s_cselect_b64 s[12:13], -1, 0
	s_waitcnt lgkmcnt(0)
	v_mfma_f32_16x16x32_bf16 v[40:43], v[70:73], v[76:79], v[40:43]
	s_mov_b64 s[10:11], -1
	s_and_b64 vcc, exec, s[12:13]
	s_cbranch_vccnz .LBB0_375

; #define LAS __attribute__((address_space(3)))
; __device__ __forceinline__ unsigned pk2(float lo, float hi) { unsigned r; asm("v_cvt_pk_bf16_f32 %0, %1, %2" : "=v"(r) : "v"(lo), "v"(hi)); return r; }
; __device__ __forceinline__ f32x4 mfma16(bf16x8 a, bf16x8 b, f32x4 c) { return __builtin_amdgcn_mfma_f32_16x16x32_bf16(a, b, c, 0, 0, 0); }
; __device__ __forceinline__ void attn_unit(LAS unsigned char* lds, const bf16* P, bf16* Y, const float* gq, const float* gk, int b, int h, int qb, int tid, int wid, int lane, ...
;     ...
;                             const float x2 = r[3], x1 = x2 * r[2], x0 = x1 * r[1], T = x0 * r[0];
;                             const float A_ = __shfl_xor(T, 16), Bp = T * A_, Cc = __shfl_xor(Bp, 32);
;                             const float Xq = quad == 3 ? 1.0f : (quad == 2 ? A_ : (quad == 1 ? Cc : A_ * Cc));
;                             const float Yv = Xq * R;
;                             av[u][3] = be[3] * Yv; av[u][2] = be[2] * (x2 * Yv); av[u][1] = be[1] * (x1 * Yv); av[u][0] = be[0] * (x0 * Yv);
;                             R *= Bp * Cc;
;                         }
;                     }
;                     const bf16x8 Bf = mk8(pk2(av[0][0], av[0][1]), pk2(av[0][2], av[0][3]), pk2(av[1][0], av[1][1]), pk2(av[1][2], av[1][3]));
; #pragma unroll
;                     for (int dt = 0; dt < 4; ++dt) {
;                         const v2u lo = *(const LAS v2u*)(Vt + (16 * dt + tq) * 136 + 32 * p + 4 * quad), hi = *(const LAS v2u*)(Vt + (16 * dt + tq) * 136 + 32 * p + 16 + 4 * quad);
;                         O[dt] = mfma16(mk8(lo.x, lo.y, hi.x, hi.y), Bf, O[dt]);
;                     }
;                     if (__ballot(R >= 1e-20f) == 0ull) wdone = true;
.LBB0_518:
	v_mul_f32_e32 v82, v75, v74
	v_mul_f32_e32 v81, v81, v82
	v_mul_f32_e32 v69, v80, v81
	ds_bpermute_b32 v83, v99, v69
	s_waitcnt lgkmcnt(0)
	v_mul_f32_e32 v69, v69, v83
	ds_bpermute_b32 v74, v122, v69
	s_waitcnt lgkmcnt(0)
	v_fma_f32 v83, v83, v252, v253
	v_fma_f32 v80, v74, v254, v255
	v_mul_f32_e32 v80, v83, v80
	v_mul_f32_e32 v105, v107, v80
	v_mul_f32_e32 v143, v82, v105
	v_mul_f32_e32 v80, v81, v105
	v_mul_f32_e32 v79, v79, v143
	v_mul_f32_e32 v75, v75, v105
	v_mul_f32_e32 v78, v78, v80
	v_mul_f32_e32 v75, v76, v75
	v_cvt_pk_bf16_f32 v76, v78, v79
	v_cvt_pk_bf16_f32 v79, v70, v71
	v_add_u32_e32 v70, 0x5800, v131
	v_cvt_pk_bf16_f32 v78, v72, v73
	ds_read2_b64 v[70:73], v70 offset0:32 offset1:36
	v_mul_f32_e32 v77, v77, v105
	v_cvt_pk_bf16_f32 v77, v75, v77
	v_add_u32_e32 v80, 0x4800, v131
	ds_read2_b64 v[80:83], v80 offset1:4
	s_waitcnt lgkmcnt(1)
	v_mfma_f32_16x16x32_bf16 v[48:51], v[70:73], v[76:79], v[48:51]
	v_add_u32_e32 v70, 0x6800, v131
	ds_read2_b64 v[70:73], v70 offset0:64 offset1:68
	v_mul_f32_e32 v69, v69, v74
	s_waitcnt lgkmcnt(0)
	v_mfma_f32_16x16x32_bf16 v[44:47], v[70:73], v[76:79], v[44:47]
	v_add_u32_e32 v70, 0x4800, v132
	ds_read2_b64 v[70:73], v70 offset1:4
	v_mul_f32_e32 v107, v107, v69
	v_mfma_f32_16x16x32_bf16 v[52:55], v[80:83], v[76:79], v[52:55]
	v_cmp_le_f32_e32 vcc, s53, v107
	s_cmp_eq_u64 vcc, 0
	s_cselect_b64 s[10:11], -1, 0
	s_waitcnt lgkmcnt(0)
	v_mfma_f32_16x16x32_bf16 v[40:43], v[70:73], v[76:79], v[40:43]
	s_nor_b64 s[14:15], s[8:9], s[10:11]
	s_and_saveexec_b64 s[12:13], s[14:15]
	s_cbranch_execnz .LBB0_376
	s_branch .LBB0_377

; __device__ __forceinline__ void attn_unit(LAS unsigned char* lds, const bf16* P, bf16* Y, const float* gq, const float* gk, int b, int h, int qb, int tid, int wid, int lane, ...
;     ...
;                             const float x2 = r[3], x1 = x2 * r[2], x0 = x1 * r[1], T = x0 * r[0];
;                             const float A_ = __shfl_xor(T, 16), Bp = T * A_, Cc = __shfl_xor(Bp, 32);
;                             const float Xq = quad == 3 ? 1.0f : (quad == 2 ? A_ : (quad == 1 ? Cc : A_ * Cc));
;                             const float Yv = Xq * R;
;                             av[u][3] = be[3] * Yv; av[u][2] = be[2] * (x2 * Yv); av[u][1] = be[1] * (x1 * Yv); av[u][0] = be[0] * (x0 * Yv);
;                             R *= Bp * Cc;
.LBB0_859:
	v_mul_f32_e32 v47, v45, v44
	v_mul_f32_e32 v46, v49, v47
	v_mul_f32_e32 v44, v48, v46
	ds_bpermute_b32 v48, v123, v44
	s_waitcnt lgkmcnt(0)
	v_mul_f32_e32 v44, v44, v48
	ds_bpermute_b32 v50, v124, v44
	s_waitcnt lgkmcnt(0)
	v_fma_f32 v48, v48, v252, v253
	v_fma_f32 v49, v50, v254, v255
	v_mul_f32_e32 v49, v48, v49
	v_mul_f32_e32 v48, v45, v49
	v_pk_mul_f32 v[40:41], v[40:41], v[48:49]
	v_mov_b32_e32 v48, v49
	v_pk_mul_f32 v[46:47], v[46:47], v[48:49] op_sel_hi:[1,0]
	s_waitcnt lgkmcnt(0)
	v_mul_f32_e32 v69, v44, v50
	v_pk_mul_f32 v[42:43], v[42:43], v[46:47]
	s_branch .LBB0_868

; #define LAS __attribute__((address_space(3)))
; __device__ __forceinline__ unsigned pk2(float lo, float hi) { unsigned r; asm("v_cvt_pk_bf16_f32 %0, %1, %2" : "=v"(r) : "v"(lo), "v"(hi)); return r; }
; __device__ __forceinline__ f32x4 mfma16(bf16x8 a, bf16x8 b, f32x4 c) { return __builtin_amdgcn_mfma_f32_16x16x32_bf16(a, b, c, 0, 0, 0); }
; __device__ __forceinline__ void attn_unit(LAS unsigned char* lds, const bf16* P, bf16* Y, const float* gq, const float* gk, int b, int h, int qb, int tid, int wid, int lane, ...
;     ...
;                             const float x2 = r[3], x1 = x2 * r[2], x0 = x1 * r[1], T = x0 * r[0];
;                             const float A_ = __shfl_xor(T, 16), Bp = T * A_, Cc = __shfl_xor(Bp, 32);
;                             const float Xq = quad == 3 ? 1.0f : (quad == 2 ? A_ : (quad == 1 ? Cc : A_ * Cc));
;                             const float Yv = Xq * R;
;                             av[u][3] = be[3] * Yv; av[u][2] = be[2] * (x2 * Yv); av[u][1] = be[1] * (x1 * Yv); av[u][0] = be[0] * (x0 * Yv);
;                             R *= Bp * Cc;
;                         }
;                     }
;                     const bf16x8 Bf = mk8(pk2(av[0][0], av[0][1]), pk2(av[0][2], av[0][3]), pk2(av[1][0], av[1][1]), pk2(av[1][2], av[1][3]));
; #pragma unroll
;                     for (int dt = 0; dt < 4; ++dt) {
;                         const v2u lo = *(const LAS v2u*)(Vt + (16 * dt + tq) * 136 + 32 * p + 4 * quad), hi = *(const LAS v2u*)(Vt + (16 * dt + tq) * 136 + 32 * p + 16 + 4 * quad);
;                         O[dt] = mfma16(mk8(lo.x, lo.y, hi.x, hi.y), Bf, O[dt]);
;                     }
;                     if (__ballot(R >= 1e-20f) == 0ull) wdone = true;
.LBB0_870:
	v_mul_f32_e32 v44, v45, v44
	v_mul_f32_e32 v51, v51, v44
	v_mul_f32_e32 v50, v50, v51
	ds_bpermute_b32 v52, v123, v50
	s_waitcnt lgkmcnt(0)
	v_mul_f32_e32 v70, v50, v52
	ds_bpermute_b32 v71, v124, v70
	s_waitcnt lgkmcnt(0)
	v_fma_f32 v52, v52, v252, v253
	v_fma_f32 v50, v71, v254, v255
	v_mul_f32_e32 v50, v52, v50
	v_mul_f32_e32 v54, v69, v50
	v_mul_f32_e32 v50, v51, v54
	v_mul_f32_e32 v48, v48, v50
	v_add_u32_e32 v50, 0x4800, v133
	v_cvt_pk_bf16_f32 v75, v40, v41
	v_add_u32_e32 v40, 0x5800, v133
	ds_read2_b64 v[50:53], v50 offset0:24 offset1:28
	v_cvt_pk_bf16_f32 v74, v42, v43
	ds_read2_b64 v[40:43], v40 offset0:56 offset1:60
	v_mul_f32_e32 v44, v44, v54
	v_mul_f32_e32 v45, v45, v54
	v_mul_f32_e32 v44, v49, v44
	v_mul_f32_e32 v45, v46, v45
	v_mul_f32_e32 v46, v47, v54
	v_cvt_pk_bf16_f32 v72, v48, v44
	v_cvt_pk_bf16_f32 v73, v45, v46
	s_waitcnt lgkmcnt(2)
	v_mul_f32_e32 v70, v70, v71
	s_waitcnt lgkmcnt(1)
	v_mfma_f32_16x16x32_bf16 v[52:55], v[50:53], v[72:75], 0
	v_mul_f32_e32 v107, v69, v70
	v_cmp_le_f32_e32 vcc, s67, v107
	s_cmp_eq_u64 vcc, 0
	s_waitcnt lgkmcnt(0)
	v_mfma_f32_16x16x32_bf16 v[48:51], v[40:43], v[72:75], 0
	v_add_u32_e32 v40, 0x6800, v133
	ds_read2_b64 v[40:43], v40 offset0:88 offset1:92
	s_cselect_b64 s[12:13], -1, 0
	s_waitcnt lgkmcnt(0)
	v_mfma_f32_16x16x32_bf16 v[44:47], v[40:43], v[72:75], 0
	v_add_u32_e32 v40, 0x4800, v134
	ds_read2_b64 v[40:43], v40 offset0:24 offset1:28
	s_waitcnt lgkmcnt(0)
	v_mfma_f32_16x16x32_bf16 v[40:43], v[40:43], v[72:75], 0
	s_or_b64 s[10:11], s[22:23], s[12:13]
	s_and_b64 vcc, exec, s[10:11]
	s_cbranch_vccnz .LBB0_897

; __device__ __forceinline__ void attn_unit(LAS unsigned char* lds, const bf16* P, bf16* Y, const float* gq, const float* gk, int b, int h, int qb, int tid, int wid, int lane, ...
;     ...
;                             const float x2 = r[3], x1 = x2 * r[2], x0 = x1 * r[1], T = x0 * r[0];
;                             const float A_ = __shfl_xor(T, 16), Bp = T * A_, Cc = __shfl_xor(Bp, 32);
;                             const float Xq = quad == 3 ? 1.0f : (quad == 2 ? A_ : (quad == 1 ? Cc : A_ * Cc));
;                             const float Yv = Xq * R;
;                             av[u][3] = be[3] * Yv; av[u][2] = be[2] * (x2 * Yv); av[u][1] = be[1] * (x1 * Yv); av[u][0] = be[0] * (x0 * Yv);
;                             R *= Bp * Cc;
.LBB0_880:
	v_mul_f32_e32 v77, v75, v74
	v_mul_f32_e32 v76, v79, v77
	v_mul_f32_e32 v69, v78, v76
	ds_bpermute_b32 v79, v123, v69
	s_waitcnt lgkmcnt(0)
	v_mul_f32_e32 v69, v69, v79
	ds_bpermute_b32 v74, v124, v69
	s_waitcnt lgkmcnt(0)
	v_fma_f32 v79, v79, v252, v253
	v_fma_f32 v78, v74, v254, v255
	v_mul_f32_e32 v78, v79, v78
	v_mul_f32_e32 v79, v107, v78
	v_mul_f32_e32 v78, v75, v79
	v_pk_mul_f32 v[70:71], v[70:71], v[78:79]
	v_mov_b32_e32 v78, v79
	v_pk_mul_f32 v[76:77], v[76:77], v[78:79] op_sel_hi:[1,0]
	s_waitcnt lgkmcnt(0)
	v_mul_f32_e32 v69, v69, v74
	v_pk_mul_f32 v[72:73], v[72:73], v[76:77]
	v_mul_f32_e32 v107, v107, v69
	s_branch .LBB0_888

; #define LAS __attribute__((address_space(3)))
; __device__ __forceinline__ unsigned pk2(float lo, float hi) { unsigned r; asm("v_cvt_pk_bf16_f32 %0, %1, %2" : "=v"(r) : "v"(lo), "v"(hi)); return r; }
; __device__ __forceinline__ f32x4 mfma16(bf16x8 a, bf16x8 b, f32x4 c) { return __builtin_amdgcn_mfma_f32_16x16x32_bf16(a, b, c, 0, 0, 0); }
; __device__ __forceinline__ void attn_unit(LAS unsigned char* lds, const bf16* P, bf16* Y, const float* gq, const float* gk, int b, int h, int qb, int tid, int wid, int lane, ...
;     ...
;                             const float x2 = r[3], x1 = x2 * r[2], x0 = x1 * r[1], T = x0 * r[0];
;                             const float A_ = __shfl_xor(T, 16), Bp = T * A_, Cc = __shfl_xor(Bp, 32);
;                             const float Xq = quad == 3 ? 1.0f : (quad == 2 ? A_ : (quad == 1 ? Cc : A_ * Cc));
;                             const float Yv = Xq * R;
;                             av[u][3] = be[3] * Yv; av[u][2] = be[2] * (x2 * Yv); av[u][1] = be[1] * (x1 * Yv); av[u][0] = be[0] * (x0 * Yv);
;                             R *= Bp * Cc;
;                         }
;                     }
;                     const bf16x8 Bf = mk8(pk2(av[0][0], av[0][1]), pk2(av[0][2], av[0][3]), pk2(av[1][0], av[1][1]), pk2(av[1][2], av[1][3]));
; #pragma unroll
;                     for (int dt = 0; dt < 4; ++dt) {
;                         const v2u lo = *(const LAS v2u*)(Vt + (16 * dt + tq) * 136 + 32 * p + 4 * quad), hi = *(const LAS v2u*)(Vt + (16 * dt + tq) * 136 + 32 * p + 16 + 4 * quad);
;                         O[dt] = mfma16(mk8(lo.x, lo.y, hi.x, hi.y), Bf, O[dt]);
;                     }
;                     if (__ballot(R >= 1e-20f) == 0ull) wdone = true;
.LBB0_890:
	v_mul_f32_e32 v82, v75, v74
	v_mul_f32_e32 v81, v81, v82
	v_mul_f32_e32 v69, v80, v81
	ds_bpermute_b32 v83, v123, v69
	s_waitcnt lgkmcnt(0)
	v_mul_f32_e32 v69, v69, v83
	ds_bpermute_b32 v74, v124, v69
	s_waitcnt lgkmcnt(0)
	v_fma_f32 v83, v83, v252, v253
	v_fma_f32 v80, v74, v254, v255
	v_mul_f32_e32 v80, v83, v80
	v_mul_f32_e32 v105, v107, v80
	v_mul_f32_e32 v146, v82, v105
	v_mul_f32_e32 v80, v81, v105
	v_mul_f32_e32 v79, v79, v146
	v_mul_f32_e32 v75, v75, v105
	v_mul_f32_e32 v78, v78, v80
	v_mul_f32_e32 v75, v76, v75
	v_cvt_pk_bf16_f32 v76, v78, v79
	v_cvt_pk_bf16_f32 v79, v70, v71
	v_add_u32_e32 v70, 0x5800, v133
	v_cvt_pk_bf16_f32 v78, v72, v73
	ds_read2_b64 v[70:73], v70 offset0:48 offset1:52
	v_mul_f32_e32 v77, v77, v105
	v_cvt_pk_bf16_f32 v77, v75, v77
	v_add_u32_e32 v80, 0x4800, v133
	ds_read2_b64 v[80:83], v80 offset0:16 offset1:20
	s_waitcnt lgkmcnt(1)
	v_mfma_f32_16x16x32_bf16 v[48:51], v[70:73], v[76:79], v[48:51]
	v_add_u32_e32 v70, 0x6800, v133
	ds_read2_b64 v[70:73], v70 offset0:80 offset1:84
	v_mul_f32_e32 v69, v69, v74
	s_waitcnt lgkmcnt(0)
	v_mfma_f32_16x16x32_bf16 v[44:47], v[70:73], v[76:79], v[44:47]
	v_add_u32_e32 v70, 0x4800, v134
	ds_read2_b64 v[70:73], v70 offset0:16 offset1:20
	v_mul_f32_e32 v107, v107, v69
	v_mfma_f32_16x16x32_bf16 v[52:55], v[80:83], v[76:79], v[52:55]
	v_cmp_le_f32_e32 vcc, s67, v107
	s_cmp_eq_u64 vcc, 0
	s_cselect_b64 s[12:13], -1, 0
	s_waitcnt lgkmcnt(0)
	v_mfma_f32_16x16x32_bf16 v[40:43], v[70:73], v[76:79], v[40:43]

; __device__ __forceinline__ void attn_unit(LAS unsigned char* lds, const bf16* P, bf16* Y, const float* gq, const float* gk, int b, int h, int qb, int tid, int wid, int lane, ...
;     ...
;                             const float x2 = r[3], x1 = x2 * r[2], x0 = x1 * r[1], T = x0 * r[0];
;                             const float A_ = __shfl_xor(T, 16), Bp = T * A_, Cc = __shfl_xor(Bp, 32);
;                             const float Xq = quad == 3 ? 1.0f : (quad == 2 ? A_ : (quad == 1 ? Cc : A_ * Cc));
;                             const float Yv = Xq * R;
;                             av[u][3] = be[3] * Yv; av[u][2] = be[2] * (x2 * Yv); av[u][1] = be[1] * (x1 * Yv); av[u][0] = be[0] * (x0 * Yv);
;                             R *= Bp * Cc;
.LBB0_914:
	v_mul_f32_e32 v65, v57, v56
	v_mul_f32_e32 v64, v63, v65
	v_mul_f32_e32 v56, v62, v64
	ds_bpermute_b32 v66, v123, v56
	s_waitcnt lgkmcnt(0)
	v_mul_f32_e32 v62, v56, v66
	ds_bpermute_b32 v63, v124, v62
	s_waitcnt lgkmcnt(0)
	v_fma_f32 v66, v66, v252, v253
	v_fma_f32 v56, v63, v254, v255
	v_mul_f32_e32 v56, v66, v56
	v_mul_f32_e32 v67, v107, v56
	v_mul_f32_e32 v66, v57, v67
	v_pk_mul_f32 v[56:57], v[60:61], v[66:67]
	v_mov_b32_e32 v60, v67
	v_pk_mul_f32 v[60:61], v[64:65], v[60:61] op_sel_hi:[1,0]
	s_nop 0
	v_pk_mul_f32 v[58:59], v[58:59], v[60:61]
	s_waitcnt lgkmcnt(0)
	v_mul_f32_e32 v60, v62, v63
	v_mul_f32_e32 v107, v107, v60
	s_branch .LBB0_922

; #define LAS __attribute__((address_space(3)))
; __device__ __forceinline__ unsigned pk2(float lo, float hi) { unsigned r; asm("v_cvt_pk_bf16_f32 %0, %1, %2" : "=v"(r) : "v"(lo), "v"(hi)); return r; }
; __device__ __forceinline__ f32x4 mfma16(bf16x8 a, bf16x8 b, f32x4 c) { return __builtin_amdgcn_mfma_f32_16x16x32_bf16(a, b, c, 0, 0, 0); }
; __device__ __forceinline__ void attn_unit(LAS unsigned char* lds, const bf16* P, bf16* Y, const float* gq, const float* gk, int b, int h, int qb, int tid, int wid, int lane, ...
;     ...
;                             const float x2 = r[3], x1 = x2 * r[2], x0 = x1 * r[1], T = x0 * r[0];
;                             const float A_ = __shfl_xor(T, 16), Bp = T * A_, Cc = __shfl_xor(Bp, 32);
;                             const float Xq = quad == 3 ? 1.0f : (quad == 2 ? A_ : (quad == 1 ? Cc : A_ * Cc));
;                             const float Yv = Xq * R;
;                             av[u][3] = be[3] * Yv; av[u][2] = be[2] * (x2 * Yv); av[u][1] = be[1] * (x1 * Yv); av[u][0] = be[0] * (x0 * Yv);
;                             R *= Bp * Cc;
;                         }
;                     }
;                     const bf16x8 Bf = mk8(pk2(av[0][0], av[0][1]), pk2(av[0][2], av[0][3]), pk2(av[1][0], av[1][1]), pk2(av[1][2], av[1][3]));
; #pragma unroll
;                     for (int dt = 0; dt < 4; ++dt) {
;                         const v2u lo = *(const LAS v2u*)(Vt + (16 * dt + tq) * 136 + 32 * p + 4 * quad), hi = *(const LAS v2u*)(Vt + (16 * dt + tq) * 136 + 32 * p + 16 + 4 * quad);
;                         O[dt] = mfma16(mk8(lo.x, lo.y, hi.x, hi.y), Bf, O[dt]);
;                     }
;                     if (__ballot(R >= 1e-20f) == 0ull) wdone = true;
.LBB0_924:
	v_mul_f32_e32 v60, v61, v60
	v_mul_f32_e32 v67, v67, v60
	v_mul_f32_e32 v66, v66, v67
	ds_bpermute_b32 v86, v123, v66
	s_waitcnt lgkmcnt(0)
	v_mul_f32_e32 v84, v66, v86
	ds_bpermute_b32 v85, v124, v84
	s_waitcnt lgkmcnt(0)
	v_fma_f32 v86, v86, v252, v253
	v_fma_f32 v66, v85, v254, v255
	v_mul_f32_e32 v66, v86, v66
	v_mul_f32_e32 v66, v107, v66
	v_mul_f32_e32 v61, v61, v66
	v_mul_f32_e32 v61, v62, v61
	v_mul_f32_e32 v62, v63, v66
	v_cvt_pk_bf16_f32 v63, v56, v57
	v_add_u32_e32 v56, 0x4800, v133
	v_cvt_pk_bf16_f32 v61, v61, v62
	v_cvt_pk_bf16_f32 v62, v58, v59
	ds_read2_b64 v[56:59], v56 offset0:24 offset1:28
	v_mul_f32_e32 v60, v60, v66
	v_mul_f32_e32 v67, v67, v66
	v_mul_f32_e32 v60, v65, v60
	v_mul_f32_e32 v64, v64, v67
	v_cvt_pk_bf16_f32 v60, v64, v60
	s_waitcnt lgkmcnt(1)
	v_mul_f32_e32 v84, v84, v85
	s_waitcnt lgkmcnt(0)
	v_mfma_f32_16x16x32_bf16 v[52:55], v[56:59], v[60:63], v[52:55]
	v_add_u32_e32 v56, 0x5800, v133
	ds_read2_b64 v[56:59], v56 offset0:56 offset1:60
	v_mul_f32_e32 v84, v107, v84
	v_cmp_le_f32_e32 vcc, s67, v84
	s_waitcnt lgkmcnt(0)
	v_mfma_f32_16x16x32_bf16 v[48:51], v[56:59], v[60:63], v[48:51]
	v_add_u32_e32 v56, 0x6800, v133
	ds_read2_b64 v[56:59], v56 offset0:88 offset1:92
	s_cmp_eq_u64 vcc, 0
	s_waitcnt lgkmcnt(0)
	v_mfma_f32_16x16x32_bf16 v[44:47], v[56:59], v[60:63], v[44:47]
	v_add_u32_e32 v56, 0x4800, v134
	ds_read2_b64 v[56:59], v56 offset0:24 offset1:28
	s_cselect_b64 s[10:11], -1, 0
	s_waitcnt lgkmcnt(0)
	v_mfma_f32_16x16x32_bf16 v[40:43], v[56:59], v[60:63], v[40:43]
	v_mov_b32_e32 v107, v84

; #define LAS __attribute__((address_space(3)))
; __device__ __forceinline__ unsigned pk2(float lo, float hi) { unsigned r; asm("v_cvt_pk_bf16_f32 %0, %1, %2" : "=v"(r) : "v"(lo), "v"(hi)); return r; }
; __device__ __forceinline__ f32x4 mfma16(bf16x8 a, bf16x8 b, f32x4 c) { return __builtin_amdgcn_mfma_f32_16x16x32_bf16(a, b, c, 0, 0, 0); }
; __device__ __forceinline__ void attn_unit(LAS unsigned char* lds, const bf16* P, bf16* Y, const float* gq, const float* gk, int b, int h, int qb, int tid, int wid, int lane, ...
;     ...
;                             const float x2 = r[3], x1 = x2 * r[2], x0 = x1 * r[1], T = x0 * r[0];
;                             const float A_ = __shfl_xor(T, 16), Bp = T * A_, Cc = __shfl_xor(Bp, 32);
;                             const float Xq = quad == 3 ? 1.0f : (quad == 2 ? A_ : (quad == 1 ? Cc : A_ * Cc));
;                             const float Yv = Xq * R;
;                             av[u][3] = be[3] * Yv; av[u][2] = be[2] * (x2 * Yv); av[u][1] = be[1] * (x1 * Yv); av[u][0] = be[0] * (x0 * Yv);
;                             R *= Bp * Cc;
;                         }
;                     }
;                     const bf16x8 Bf = mk8(pk2(av[0][0], av[0][1]), pk2(av[0][2], av[0][3]), pk2(av[1][0], av[1][1]), pk2(av[1][2], av[1][3]));
; #pragma unroll
;                     for (int dt = 0; dt < 4; ++dt) {
;                         const v2u lo = *(const LAS v2u*)(Vt + (16 * dt + tq) * 136 + 32 * p + 4 * quad), hi = *(const LAS v2u*)(Vt + (16 * dt + tq) * 136 + 32 * p + 16 + 4 * quad);
;                         O[dt] = mfma16(mk8(lo.x, lo.y, hi.x, hi.y), Bf, O[dt]);
;                     }
;                     if (__ballot(R >= 1e-20f) == 0ull) wdone = true;
.LBB0_945:
	v_mul_f32_e32 v60, v61, v60
	v_mul_f32_e32 v67, v67, v60
	v_mul_f32_e32 v66, v66, v67
	ds_bpermute_b32 v86, v123, v66
	s_waitcnt lgkmcnt(0)
	v_mul_f32_e32 v84, v66, v86
	ds_bpermute_b32 v85, v124, v84
	s_waitcnt lgkmcnt(0)
	v_fma_f32 v86, v86, v252, v253
	v_fma_f32 v66, v85, v254, v255
	v_mul_f32_e32 v66, v86, v66
	v_mul_f32_e32 v66, v107, v66
	v_mul_f32_e32 v61, v61, v66
	v_mul_f32_e32 v61, v62, v61
	v_mul_f32_e32 v62, v63, v66
	v_cvt_pk_bf16_f32 v63, v56, v57
	v_add_u32_e32 v56, 0x4800, v133
	v_cvt_pk_bf16_f32 v61, v61, v62
	v_cvt_pk_bf16_f32 v62, v58, v59
	ds_read2_b64 v[56:59], v56 offset0:16 offset1:20
	v_mul_f32_e32 v60, v60, v66
	v_mul_f32_e32 v67, v67, v66
	v_mul_f32_e32 v60, v65, v60
	v_mul_f32_e32 v64, v64, v67
	v_cvt_pk_bf16_f32 v60, v64, v60
	s_waitcnt lgkmcnt(1)
	v_mul_f32_e32 v84, v84, v85
	s_waitcnt lgkmcnt(0)
	v_mfma_f32_16x16x32_bf16 v[52:55], v[56:59], v[60:63], v[52:55]
	v_add_u32_e32 v56, 0x5800, v133
	ds_read2_b64 v[56:59], v56 offset0:48 offset1:52
	v_mul_f32_e32 v84, v107, v84
	v_cmp_le_f32_e32 vcc, s67, v84
	s_waitcnt lgkmcnt(0)
	v_mfma_f32_16x16x32_bf16 v[48:51], v[56:59], v[60:63], v[48:51]
	v_add_u32_e32 v56, 0x6800, v133
	ds_read2_b64 v[56:59], v56 offset0:80 offset1:84
	s_cmp_eq_u64 vcc, 0
	s_waitcnt lgkmcnt(0)
	v_mfma_f32_16x16x32_bf16 v[44:47], v[56:59], v[60:63], v[44:47]
	v_add_u32_e32 v56, 0x4800, v134
	ds_read2_b64 v[56:59], v56 offset0:16 offset1:20
	s_cselect_b64 s[10:11], -1, 0
	s_waitcnt lgkmcnt(0)
	v_mfma_f32_16x16x32_bf16 v[40:43], v[56:59], v[60:63], v[40:43]
	v_mov_b32_e32 v107, v84

; #define LAS __attribute__((address_space(3)))
; __device__ __forceinline__ unsigned pk2(float lo, float hi) { unsigned r; asm("v_cvt_pk_bf16_f32 %0, %1, %2" : "=v"(r) : "v"(lo), "v"(hi)); return r; }
; __device__ __forceinline__ f32x4 mfma16(bf16x8 a, bf16x8 b, f32x4 c) { return __builtin_amdgcn_mfma_f32_16x16x32_bf16(a, b, c, 0, 0, 0); }
; __device__ __forceinline__ void attn_unit(LAS unsigned char* lds, const bf16* P, bf16* Y, const float* gq, const float* gk, int b, int h, int qb, int tid, int wid, int lane, ...
;     ...
;                             const float x2 = r[3], x1 = x2 * r[2], x0 = x1 * r[1], T = x0 * r[0];
;                             const float A_ = __shfl_xor(T, 16), Bp = T * A_, Cc = __shfl_xor(Bp, 32);
;                             const float Xq = quad == 3 ? 1.0f : (quad == 2 ? A_ : (quad == 1 ? Cc : A_ * Cc));
;                             const float Yv = Xq * R;
;                             av[u][3] = be[3] * Yv; av[u][2] = be[2] * (x2 * Yv); av[u][1] = be[1] * (x1 * Yv); av[u][0] = be[0] * (x0 * Yv);
;                             R *= Bp * Cc;
;                         }
;                     }
;                     const bf16x8 Bf = mk8(pk2(av[0][0], av[0][1]), pk2(av[0][2], av[0][3]), pk2(av[1][0], av[1][1]), pk2(av[1][2], av[1][3]));
; #pragma unroll
;                     for (int dt = 0; dt < 4; ++dt) {
;                         const v2u lo = *(const LAS v2u*)(Vt + (16 * dt + tq) * 136 + 32 * p + 4 * quad), hi = *(const LAS v2u*)(Vt + (16 * dt + tq) * 136 + 32 * p + 16 + 4 * quad);
;                         O[dt] = mfma16(mk8(lo.x, lo.y, hi.x, hi.y), Bf, O[dt]);
;                     }
;                     if (__ballot(R >= 1e-20f) == 0ull) wdone = true;
.LBB0_966:
	v_mul_f32_e32 v60, v61, v60
	v_mul_f32_e32 v67, v67, v60
	v_mul_f32_e32 v66, v66, v67
	ds_bpermute_b32 v86, v123, v66
	s_waitcnt lgkmcnt(0)
	v_mul_f32_e32 v84, v66, v86
	ds_bpermute_b32 v85, v124, v84
	s_waitcnt lgkmcnt(0)
	v_fma_f32 v86, v86, v252, v253
	v_fma_f32 v66, v85, v254, v255
	v_mul_f32_e32 v66, v86, v66
	v_mul_f32_e32 v66, v107, v66
	v_mul_f32_e32 v61, v61, v66
	v_mul_f32_e32 v61, v62, v61
	v_mul_f32_e32 v62, v63, v66
	v_cvt_pk_bf16_f32 v63, v56, v57
	v_add_u32_e32 v56, 0x4800, v133
	v_cvt_pk_bf16_f32 v61, v61, v62
	v_cvt_pk_bf16_f32 v62, v58, v59
	ds_read2_b64 v[56:59], v56 offset0:8 offset1:12
	v_mul_f32_e32 v60, v60, v66
	v_mul_f32_e32 v67, v67, v66
	v_mul_f32_e32 v60, v65, v60
	v_mul_f32_e32 v64, v64, v67
	v_cvt_pk_bf16_f32 v60, v64, v60
	s_waitcnt lgkmcnt(1)
	v_mul_f32_e32 v84, v84, v85
	s_waitcnt lgkmcnt(0)
	v_mfma_f32_16x16x32_bf16 v[52:55], v[56:59], v[60:63], v[52:55]
	v_add_u32_e32 v56, 0x5800, v133
	ds_read2_b64 v[56:59], v56 offset0:40 offset1:44
	v_mul_f32_e32 v84, v107, v84
	v_cmp_le_f32_e32 vcc, s67, v84
	s_waitcnt lgkmcnt(0)
	v_mfma_f32_16x16x32_bf16 v[48:51], v[56:59], v[60:63], v[48:51]
	v_add_u32_e32 v56, 0x4800, v136
	ds_read2_b64 v[56:59], v56 offset0:8 offset1:12
	s_cmp_eq_u64 vcc, 0
	s_waitcnt lgkmcnt(0)
	v_mfma_f32_16x16x32_bf16 v[44:47], v[56:59], v[60:63], v[44:47]
	v_add_u32_e32 v56, 0x4800, v134
	ds_read2_b64 v[56:59], v56 offset0:8 offset1:12
	s_cselect_b64 s[10:11], -1, 0
	s_waitcnt lgkmcnt(0)
	v_mfma_f32_16x16x32_bf16 v[40:43], v[56:59], v[60:63], v[40:43]
	v_mov_b32_e32 v107, v84

; #define LAS __attribute__((address_space(3)))
; __device__ __forceinline__ unsigned pk2(float lo, float hi) { unsigned r; asm("v_cvt_pk_bf16_f32 %0, %1, %2" : "=v"(r) : "v"(lo), "v"(hi)); return r; }
; __device__ __forceinline__ f32x4 mfma16(bf16x8 a, bf16x8 b, f32x4 c) { return __builtin_amdgcn_mfma_f32_16x16x32_bf16(a, b, c, 0, 0, 0); }
; __device__ __forceinline__ void attn_unit(LAS unsigned char* lds, const bf16* P, bf16* Y, const float* gq, const float* gk, int b, int h, int qb, int tid, int wid, int lane, ...
;     ...
;                             const float x2 = r[3], x1 = x2 * r[2], x0 = x1 * r[1], T = x0 * r[0];
;                             const float A_ = __shfl_xor(T, 16), Bp = T * A_, Cc = __shfl_xor(Bp, 32);
;                             const float Xq = quad == 3 ? 1.0f : (quad == 2 ? A_ : (quad == 1 ? Cc : A_ * Cc));
;                             const float Yv = Xq * R;
;                             av[u][3] = be[3] * Yv; av[u][2] = be[2] * (x2 * Yv); av[u][1] = be[1] * (x1 * Yv); av[u][0] = be[0] * (x0 * Yv);
;                             R *= Bp * Cc;
;                         }
;                     }
;                     const bf16x8 Bf = mk8(pk2(av[0][0], av[0][1]), pk2(av[0][2], av[0][3]), pk2(av[1][0], av[1][1]), pk2(av[1][2], av[1][3]));
; #pragma unroll
;                     for (int dt = 0; dt < 4; ++dt) {
;                         const v2u lo = *(const LAS v2u*)(Vt + (16 * dt + tq) * 136 + 32 * p + 4 * quad), hi = *(const LAS v2u*)(Vt + (16 * dt + tq) * 136 + 32 * p + 16 + 4 * quad);
;                         O[dt] = mfma16(mk8(lo.x, lo.y, hi.x, hi.y), Bf, O[dt]);
;                     }
;                     if (__ballot(R >= 1e-20f) == 0ull) wdone = true;
.LBB0_987:
	v_mul_f32_e32 v84, v61, v60
	v_mul_f32_e32 v67, v67, v84
	v_mul_f32_e32 v60, v66, v67
	ds_bpermute_b32 v86, v123, v60
	s_waitcnt lgkmcnt(0)
	v_mul_f32_e32 v60, v60, v86
	ds_bpermute_b32 v66, v124, v60
	s_waitcnt lgkmcnt(0)
	v_fma_f32 v86, v86, v252, v253
	v_fma_f32 v85, v66, v254, v255
	v_mul_f32_e32 v85, v86, v85
	v_mul_f32_e32 v105, v107, v85
	v_mul_f32_e32 v67, v67, v105
	v_mul_f32_e32 v64, v64, v67
	v_mul_f32_e32 v67, v84, v105
	v_mul_f32_e32 v65, v65, v67
	v_mul_f32_e32 v61, v61, v105
	v_mul_f32_e32 v61, v62, v61
	v_cvt_pk_bf16_f32 v62, v64, v65
	v_cvt_pk_bf16_f32 v65, v56, v57
	v_add_u32_e32 v56, 0x5800, v133
	v_cvt_pk_bf16_f32 v64, v58, v59
	ds_read2_b64 v[56:59], v56 offset0:32 offset1:36
	v_mul_f32_e32 v63, v63, v105
	v_cvt_pk_bf16_f32 v63, v61, v63
	v_add_u32_e32 v84, 0x4800, v133
	ds_read2_b64 v[84:87], v84 offset1:4
	s_waitcnt lgkmcnt(1)
	v_mfma_f32_16x16x32_bf16 v[48:51], v[56:59], v[62:65], v[48:51]
	v_add_u32_e32 v56, 0x6800, v133
	ds_read2_b64 v[56:59], v56 offset0:64 offset1:68
	v_mul_f32_e32 v60, v60, v66
	s_waitcnt lgkmcnt(0)
	v_mfma_f32_16x16x32_bf16 v[44:47], v[56:59], v[62:65], v[44:47]
	v_add_u32_e32 v56, 0x4800, v134
	ds_read2_b64 v[56:59], v56 offset1:4
	v_mul_f32_e32 v107, v107, v60
	v_mfma_f32_16x16x32_bf16 v[52:55], v[84:87], v[62:65], v[52:55]
	v_cmp_le_f32_e32 vcc, s67, v107
	s_cmp_eq_u64 vcc, 0
	s_cselect_b64 s[10:11], -1, 0
	s_waitcnt lgkmcnt(0)
	v_mfma_f32_16x16x32_bf16 v[40:43], v[56:59], v[62:65], v[40:43]

; #define LAS __attribute__((address_space(3)))
; __device__ __forceinline__ unsigned pk2(float lo, float hi) { unsigned r; asm("v_cvt_pk_bf16_f32 %0, %1, %2" : "=v"(r) : "v"(lo), "v"(hi)); return r; }
; __device__ __forceinline__ f32x4 mfma16(bf16x8 a, bf16x8 b, f32x4 c) { return __builtin_amdgcn_mfma_f32_16x16x32_bf16(a, b, c, 0, 0, 0); }
; __device__ __forceinline__ void attn_unit(LAS unsigned char* lds, const bf16* P, bf16* Y, const float* gq, const float* gk, int b, int h, int qb, int tid, int wid, int lane, ...
;     ...
;                             const float x2 = r[3], x1 = x2 * r[2], x0 = x1 * r[1], T = x0 * r[0];
;                             const float A_ = __shfl_xor(T, 16), Bp = T * A_, Cc = __shfl_xor(Bp, 32);
;                             const float Xq = quad == 3 ? 1.0f : (quad == 2 ? A_ : (quad == 1 ? Cc : A_ * Cc));
;                             const float Yv = Xq * R;
;                             av[u][3] = be[3] * Yv; av[u][2] = be[2] * (x2 * Yv); av[u][1] = be[1] * (x1 * Yv); av[u][0] = be[0] * (x0 * Yv);
;                             R *= Bp * Cc;
;                         }
;                     }
;                     const bf16x8 Bf = mk8(pk2(av[0][0], av[0][1]), pk2(av[0][2], av[0][3]), pk2(av[1][0], av[1][1]), pk2(av[1][2], av[1][3]));
; #pragma unroll
;                     for (int dt = 0; dt < 4; ++dt) {
;                         const v2u lo = *(const LAS v2u*)(Vt + (16 * dt + tq) * 136 + 32 * p + 4 * quad), hi = *(const LAS v2u*)(Vt + (16 * dt + tq) * 136 + 32 * p + 16 + 4 * quad);
;                         O[dt] = mfma16(mk8(lo.x, lo.y, hi.x, hi.y), Bf, O[dt]);
;                     }
;                     if (__ballot(R >= 1e-20f) == 0ull) wdone = true;
.LBB0_1022:
	v_mul_f32_e32 v82, v75, v74
	v_mul_f32_e32 v81, v81, v82
	v_mul_f32_e32 v69, v80, v81
	ds_bpermute_b32 v83, v123, v69
	s_waitcnt lgkmcnt(0)
	v_mul_f32_e32 v69, v69, v83
	ds_bpermute_b32 v74, v124, v69
	s_waitcnt lgkmcnt(0)
	v_fma_f32 v83, v83, v252, v253
	v_fma_f32 v80, v74, v254, v255
	v_mul_f32_e32 v80, v83, v80
	v_mul_f32_e32 v105, v107, v80
	v_mul_f32_e32 v146, v82, v105
	v_mul_f32_e32 v80, v81, v105
	v_mul_f32_e32 v79, v79, v146
	v_mul_f32_e32 v75, v75, v105
	v_mul_f32_e32 v78, v78, v80
	v_mul_f32_e32 v75, v76, v75
	v_cvt_pk_bf16_f32 v76, v78, v79
	v_cvt_pk_bf16_f32 v79, v70, v71
	v_add_u32_e32 v70, 0x5800, v133
	v_cvt_pk_bf16_f32 v78, v72, v73
	ds_read2_b64 v[70:73], v70 offset0:40 offset1:44
	v_mul_f32_e32 v77, v77, v105
	v_cvt_pk_bf16_f32 v77, v75, v77
	v_add_u32_e32 v80, 0x4800, v133
	ds_read2_b64 v[80:83], v80 offset0:8 offset1:12
	s_waitcnt lgkmcnt(1)
	v_mfma_f32_16x16x32_bf16 v[48:51], v[70:73], v[76:79], v[48:51]
	v_add_u32_e32 v70, 0x4800, v136
	ds_read2_b64 v[70:73], v70 offset0:8 offset1:12
	v_mul_f32_e32 v69, v69, v74
	s_waitcnt lgkmcnt(0)
	v_mfma_f32_16x16x32_bf16 v[44:47], v[70:73], v[76:79], v[44:47]
	v_add_u32_e32 v70, 0x4800, v134
	ds_read2_b64 v[70:73], v70 offset0:8 offset1:12
	v_mul_f32_e32 v107, v107, v69
	v_mfma_f32_16x16x32_bf16 v[52:55], v[80:83], v[76:79], v[52:55]
	v_cmp_le_f32_e32 vcc, s67, v107
	s_cmp_eq_u64 vcc, 0
	s_cselect_b64 s[12:13], -1, 0
	s_waitcnt lgkmcnt(0)
	v_mfma_f32_16x16x32_bf16 v[40:43], v[70:73], v[76:79], v[40:43]
	s_mov_b64 s[10:11], -1
	s_and_b64 vcc, exec, s[12:13]
	s_cbranch_vccnz .LBB0_899

; #define LAS __attribute__((address_space(3)))
; __device__ __forceinline__ unsigned pk2(float lo, float hi) { unsigned r; asm("v_cvt_pk_bf16_f32 %0, %1, %2" : "=v"(r) : "v"(lo), "v"(hi)); return r; }
; __device__ __forceinline__ f32x4 mfma16(bf16x8 a, bf16x8 b, f32x4 c) { return __builtin_amdgcn_mfma_f32_16x16x32_bf16(a, b, c, 0, 0, 0); }
; __device__ __forceinline__ void attn_unit(LAS unsigned char* lds, const bf16* P, bf16* Y, const float* gq, const float* gk, int b, int h, int qb, int tid, int wid, int lane, ...
;     ...
;                             const float x2 = r[3], x1 = x2 * r[2], x0 = x1 * r[1], T = x0 * r[0];
;                             const float A_ = __shfl_xor(T, 16), Bp = T * A_, Cc = __shfl_xor(Bp, 32);
;                             const float Xq = quad == 3 ? 1.0f : (quad == 2 ? A_ : (quad == 1 ? Cc : A_ * Cc));
;                             const float Yv = Xq * R;
;                             av[u][3] = be[3] * Yv; av[u][2] = be[2] * (x2 * Yv); av[u][1] = be[1] * (x1 * Yv); av[u][0] = be[0] * (x0 * Yv);
;                             R *= Bp * Cc;
;                         }
;                     }
;                     const bf16x8 Bf = mk8(pk2(av[0][0], av[0][1]), pk2(av[0][2], av[0][3]), pk2(av[1][0], av[1][1]), pk2(av[1][2], av[1][3]));
; #pragma unroll
;                     for (int dt = 0; dt < 4; ++dt) {
;                         const v2u lo = *(const LAS v2u*)(Vt + (16 * dt + tq) * 136 + 32 * p + 4 * quad), hi = *(const LAS v2u*)(Vt + (16 * dt + tq) * 136 + 32 * p + 16 + 4 * quad);
;                         O[dt] = mfma16(mk8(lo.x, lo.y, hi.x, hi.y), Bf, O[dt]);
;                     }
;                     if (__ballot(R >= 1e-20f) == 0ull) wdone = true;
.LBB0_1042:
	v_mul_f32_e32 v82, v75, v74
	v_mul_f32_e32 v81, v81, v82
	v_mul_f32_e32 v69, v80, v81
	ds_bpermute_b32 v83, v123, v69
	s_waitcnt lgkmcnt(0)
	v_mul_f32_e32 v69, v69, v83
	ds_bpermute_b32 v74, v124, v69
	s_waitcnt lgkmcnt(0)
	v_fma_f32 v83, v83, v252, v253
	v_fma_f32 v80, v74, v254, v255
	v_mul_f32_e32 v80, v83, v80
	v_mul_f32_e32 v105, v107, v80
	v_mul_f32_e32 v146, v82, v105
	v_mul_f32_e32 v80, v81, v105
	v_mul_f32_e32 v79, v79, v146
	v_mul_f32_e32 v75, v75, v105
	v_mul_f32_e32 v78, v78, v80
	v_mul_f32_e32 v75, v76, v75
	v_cvt_pk_bf16_f32 v76, v78, v79
	v_cvt_pk_bf16_f32 v79, v70, v71
	v_add_u32_e32 v70, 0x5800, v133
	v_cvt_pk_bf16_f32 v78, v72, v73
	ds_read2_b64 v[70:73], v70 offset0:32 offset1:36
	v_mul_f32_e32 v77, v77, v105
	v_cvt_pk_bf16_f32 v77, v75, v77
	v_add_u32_e32 v80, 0x4800, v133
	ds_read2_b64 v[80:83], v80 offset1:4
	s_waitcnt lgkmcnt(1)
	v_mfma_f32_16x16x32_bf16 v[48:51], v[70:73], v[76:79], v[48:51]
	v_add_u32_e32 v70, 0x6800, v133
	ds_read2_b64 v[70:73], v70 offset0:64 offset1:68
	v_mul_f32_e32 v69, v69, v74
	s_waitcnt lgkmcnt(0)
	v_mfma_f32_16x16x32_bf16 v[44:47], v[70:73], v[76:79], v[44:47]
	v_add_u32_e32 v70, 0x4800, v134
	ds_read2_b64 v[70:73], v70 offset1:4
	v_mul_f32_e32 v107, v107, v69
	v_mfma_f32_16x16x32_bf16 v[52:55], v[80:83], v[76:79], v[52:55]
	v_cmp_le_f32_e32 vcc, s67, v107
	s_cmp_eq_u64 vcc, 0
	s_cselect_b64 s[10:11], -1, 0
	s_waitcnt lgkmcnt(0)
	v_mfma_f32_16x16x32_bf16 v[40:43], v[70:73], v[76:79], v[40:43]
	s_nor_b64 s[14:15], s[8:9], s[10:11]
	s_and_saveexec_b64 s[12:13], s[14:15]
	s_cbranch_execnz .LBB0_900
	s_branch .LBB0_901

; #define LAS __attribute__((address_space(3)))
; __global__ void __launch_bounds__(512, 2) hybrid_fwd(Args a) {
;     extern __shared__ __attribute__((aligned(16))) unsigned char lds_raw[];
;     LAS unsigned char* lds = (LAS unsigned char*)lds_raw;
;     const int tid = threadIdx.x, lane = tid & 63, wid = __builtin_amdgcn_readfirstlane(tid >> 6);
	.amdhsa_kernel _Z10hybrid_fwd4Args
		.amdhsa_group_segment_fixed_size 0
		.amdhsa_private_segment_fixed_size 0
		.amdhsa_kernarg_size 416
		.amdhsa_user_sgpr_count 2
		.amdhsa_user_sgpr_dispatch_ptr 0
		.amdhsa_user_sgpr_queue_ptr 0
		.amdhsa_user_sgpr_kernarg_segment_ptr 1
		.amdhsa_user_sgpr_dispatch_id 0
		.amdhsa_user_sgpr_kernarg_preload_length 0
		.amdhsa_user_sgpr_kernarg_preload_offset 0
		.amdhsa_user_sgpr_private_segment_size 0
		.amdhsa_uses_dynamic_stack 0
		.amdhsa_enable_private_segment 0
		.amdhsa_system_sgpr_workgroup_id_x 1
		.amdhsa_system_sgpr_workgroup_id_y 0
		.amdhsa_system_sgpr_workgroup_id_z 0
		.amdhsa_system_sgpr_workgroup_info 0
		.amdhsa_system_vgpr_workitem_id 2
		.amdhsa_next_free_vgpr 256
		.amdhsa_next_free_sgpr 102
		.amdhsa_accum_offset 256
		.amdhsa_reserve_vcc 1
		.amdhsa_float_round_mode_32 0
		.amdhsa_float_round_mode_16_64 0
		.amdhsa_float_denorm_mode_32 3
		.amdhsa_float_denorm_mode_16_64 3
		.amdhsa_dx10_clamp 1
		.amdhsa_ieee_mode 1
		.amdhsa_fp16_overflow 0
		.amdhsa_tg_split 0
		.amdhsa_exception_fp_ieee_invalid_op 0
		.amdhsa_exception_fp_denorm_src 0
		.amdhsa_exception_fp_ieee_div_zero 0
		.amdhsa_exception_fp_ieee_overflow 0
		.amdhsa_exception_fp_ieee_underflow 0
		.amdhsa_exception_fp_ieee_inexact 0
		.amdhsa_exception_int_div_zero 0
	.end_amdhsa_kernel

; #define LAS __attribute__((address_space(3)))
; __global__ void __launch_bounds__(512, 2) hybrid_fwd(Args a) {
;     extern __shared__ __attribute__((aligned(16))) unsigned char lds_raw[];
;     LAS unsigned char* lds = (LAS unsigned char*)lds_raw;
;     const int tid = threadIdx.x, lane = tid & 63, wid = __builtin_amdgcn_readfirstlane(tid >> 6);
amdhsa.kernels:
  - .agpr_count:     0
    .args:
      - .offset:         0
        .size:           160
        .value_kind:     by_value
      - .offset:         160
        .size:           4
        .value_kind:     hidden_block_count_x
      - .offset:         164
        .size:           4
        .value_kind:     hidden_block_count_y
      - .offset:         168
        .size:           4
        .value_kind:     hidden_block_count_z
      - .offset:         172
        .size:           2
        .value_kind:     hidden_group_size_x
      - .offset:         174
        .size:           2
        .value_kind:     hidden_group_size_y
      - .offset:         176
        .size:           2
        .value_kind:     hidden_group_size_z
      - .offset:         178
        .size:           2
        .value_kind:     hidden_remainder_x
      - .offset:         180
        .size:           2
        .value_kind:     hidden_remainder_y
      - .offset:         182
        .size:           2
        .value_kind:     hidden_remainder_z
      - .offset:         200
        .size:           8
        .value_kind:     hidden_global_offset_x
      - .offset:         208
        .size:           8
        .value_kind:     hidden_global_offset_y
      - .offset:         216
        .size:           8
        .value_kind:     hidden_global_offset_z
      - .offset:         224
        .size:           2
        .value_kind:     hidden_grid_dims
      - .offset:         248
        .size:           8
        .value_kind:     hidden_multigrid_sync_arg
      - .offset:         280
        .size:           4
        .value_kind:     hidden_dynamic_lds_size
    .group_segment_fixed_size: 0
    .kernarg_segment_align: 8
    .kernarg_segment_size: 416
    .language:       OpenCL C
    .language_version:
      - 2
      - 0
    .max_flat_workgroup_size: 512
    .name:           _Z10hybrid_fwd4Args
    .private_segment_fixed_size: 0
    .sgpr_count:     108
    .sgpr_spill_count: 158
    .symbol:         _Z10hybrid_fwd4Args.kd
    .uniform_work_group_size: 1
    .uses_dynamic_stack: false
    .vgpr_count:     256
    .vgpr_spill_count: 0
    .wavefront_size: 64
